# v26 + odd-attention step body list-rescheduled: MFMA interleaved with cvt/pk_add/exp inside each wave, waitcnts regenerated
# speedup vs baseline: 1.0027x; 1.0027x over previous
; #define LAS __attribute__((address_space(3)))
; DI unsigned pk2(float lo, float hi) { f32x2 v = {lo, hi}; bf16x2_t b = __builtin_convertvector(v, bf16x2_t); return __builtin_bit_cast(unsigned, b); }
; DI void attn_group4(f32x4 (&o)[4][4], const float (&mref)[4], float (&ls)[4], const bf16x8 (&q)[4][2], bf16x8 k00, bf16x8 k01, bf16x8 k10, bf16x8 k11,
;                     bf16x8 v0, bf16x8 v1, bf16x8 v2, bf16x8 v3) {
;     const f32x4 z = {0.f, 0.f, 0.f, 0.f};
;     constexpr float C = 0.125f * LOG2E;
;     f32x4 s0[4], s1[4];
;     __builtin_amdgcn_s_setprio(1);
; #pragma unroll
;     for (int h = 0; h < 4; ++h) { s0[h] = MFMA16(k00, q[h][0], z); s1[h] = MFMA16(k10, q[h][0], z); }
; #pragma unroll
;     for (int h = 0; h < 4; ++h) { s0[h] = MFMA16(k01, q[h][1], s0[h]); s1[h] = MFMA16(k11, q[h][1], s1[h]); }
;     __builtin_amdgcn_s_setprio(0);
;     bf16x8 pb[4];
; #pragma unroll
;     for (int h = 0; h < 4; ++h) {
;         f32x4 p0, p1;
; #pragma unroll
;         for (int e = 0; e < 4; ++e) { p0[e] = __builtin_amdgcn_exp2f(__builtin_fmaf(s0[h][e], C, -mref[h])); p1[e] = __builtin_amdgcn_exp2f(__builtin_fmaf(s1[h][e], C, -mref[h])); }
;         ls[h] += ((p0[0] + p0[1]) + (p0[2] + p0[3])) + ((p1[0] + p1[1]) + (p1[2] + p1[3]));
;         u32x4 pw; pw.x = pk2(p0[0], p0[1]); pw.y = pk2(p0[2], p0[3]); pw.z = pk2(p1[0], p1[1]); pw.w = pk2(p1[2], p1[3]);
;         pb[h] = __builtin_bit_cast(bf16x8, pw);
;     }
;     __builtin_amdgcn_s_setprio(1);
; #pragma unroll
;     for (int h = 0; h < 4; ++h) { o[h][0] = MFMA16(v0, pb[h], o[h][0]); o[h][1] = MFMA16(v1, pb[h], o[h][1]); o[h][2] = MFMA16(v2, pb[h], o[h][2]); o[h][3] = MFMA16(v3, pb[h], o[h][3]); }
;     __builtin_amdgcn_s_setprio(0);
; }
; DI void attn_odd_lds(Frame& F, const float* gk  , const float* gq  , bool with_ctx) {
;     ...
;             const LAS unsigned char* sk = F.lds + (s & 3) * AT_SLOT + bk; const LAS unsigned char* sv = F.lds + (s & 3) * AT_SLOT + bv;
; #pragma unroll
;             for (int hf = 0; hf < 2; ++hf) {
;                 const bf16x8 k00 = LDS_K(sk, hf * 32, 0, 0), k01 = LDS_K(sk, hf * 32, 0, 1), k10 = LDS_K(sk, hf * 32, 1, 0), k11 = LDS_K(sk, hf * 32, 1, 1);
;                 const bf16x8 v0 = LDS_V(sv, 0, hf * 4), v1 = LDS_V(sv, 1, hf * 4), v2 = LDS_V(sv, 2, hf * 4), v3 = LDS_V(sv, 3, hf * 4);
;                 attn_group4(o, mx, ls, q, k00, k01, k10, k11, v0, v1, v2, v3);
.LBB0_258:
	s_and_b32 s4, s17, 3
	s_mulk_i32 s4, 0x4800
	v_add_u32_e32 v98, s4, v131
	v_add_u32_e32 v165, v98, v127
	v_add3_u32 v168, v98, v128, v129
	s_setprio 1
	ds_read_b128 v[98:101], v165
	s_waitcnt lgkmcnt(0)
	v_mfma_f32_16x16x32_bf16 v[152:155], v[98:101], v[2:5], v[228:231]
	ds_read_b128 v[108:111], v165 offset:512
	ds_read_b128 v[112:115], v165 offset:2304
	v_mfma_f32_16x16x32_bf16 v[170:173], v[98:101], v[10:13], v[232:235]
	ds_read_b128 v[116:119], v165 offset:2816
	v_add_u32_e32 v195, 0x2000, v168
	v_mfma_f32_16x16x32_bf16 v[188:191], v[98:101], v[18:21], v[236:239]
	ds_read2_b64 v[136:139], v195 offset0:128 offset1:160
	v_add_u32_e32 v140, 0x2800, v168
	s_waitcnt lgkmcnt(2)
	v_mfma_f32_16x16x32_bf16 v[156:159], v[112:115], v[2:5], v[228:231]
	ds_read2_b64 v[140:143], v140 offset0:160 offset1:192
	v_add_u32_e32 v144, 0x3000, v168
	v_mfma_f32_16x16x32_bf16 v[174:177], v[112:115], v[10:13], v[232:235]
	ds_read2_b64 v[144:147], v144 offset0:192 offset1:224
	v_add_u32_e32 v148, 0x3c00, v168
	v_mfma_f32_16x16x32_bf16 v[196:199], v[112:115], v[18:21], v[236:239]
	ds_read2_b64 v[148:151], v148 offset0:96 offset1:128
	v_mfma_f32_16x16x32_bf16 v[98:101], v[98:101], v[42:45], v[240:243]
	v_mfma_f32_16x16x32_bf16 v[112:115], v[112:115], v[42:45], v[240:243]
	v_mfma_f32_16x16x32_bf16 v[152:155], v[108:111], v[6:9], v[152:155]
	s_waitcnt lgkmcnt(4)
	v_mfma_f32_16x16x32_bf16 v[156:159], v[116:119], v[6:9], v[156:159]
	v_mfma_f32_16x16x32_bf16 v[170:173], v[108:111], v[14:17], v[170:173]
	v_mfma_f32_16x16x32_bf16 v[174:177], v[116:119], v[14:17], v[174:177]
	v_mfma_f32_16x16x32_bf16 v[188:191], v[108:111], v[22:25], v[188:191]
	v_mfma_f32_16x16x32_bf16 v[196:199], v[116:119], v[22:25], v[196:199]
	v_mfma_f32_16x16x32_bf16 v[200:203], v[116:119], v[46:49], v[112:115]
	v_mfma_f32_16x16x32_bf16 v[98:101], v[108:111], v[46:49], v[98:101]
	s_nop 0
	v_exp_f32_e32 v161, v152
	v_exp_f32_e32 v167, v156
	v_exp_f32_e32 v179, v153
	v_exp_f32_e32 v185, v157
	v_exp_f32_e32 v213, v154
	v_exp_f32_e32 v215, v158
	v_exp_f32_e32 v217, v155
	v_exp_f32_e32 v219, v159
	v_exp_f32_e32 v160, v170
	v_exp_f32_e32 v166, v174
	v_exp_f32_e32 v178, v171
	v_exp_f32_e32 v184, v175
	v_exp_f32_e32 v212, v172
	v_exp_f32_e32 v214, v176
	v_exp_f32_e32 v216, v173
	v_exp_f32_e32 v218, v177
	v_exp_f32_e32 v117, v188
	v_exp_f32_e32 v109, v196
	v_exp_f32_e32 v221, v189
	v_exp_f32_e32 v113, v197
	v_exp_f32_e32 v119, v190
	v_exp_f32_e32 v111, v198
	v_exp_f32_e32 v223, v191
	v_exp_f32_e32 v116, v98
	v_exp_f32_e32 v115, v199
	v_exp_f32_e32 v108, v200
	v_exp_f32_e32 v220, v99
	v_exp_f32_e32 v112, v201
	v_exp_f32_e32 v118, v100
	v_exp_f32_e32 v110, v202
	v_exp_f32_e32 v222, v101
	v_exp_f32_e32 v114, v203
	v_cvt_pk_bf16_f32 v152, v161, v179
	v_cvt_pk_bf16_f32 v153, v213, v217
	v_cvt_pk_bf16_f32 v154, v167, v185
	v_cvt_pk_bf16_f32 v155, v215, v219
	v_cvt_pk_bf16_f32 v156, v160, v178
	v_cvt_pk_bf16_f32 v157, v212, v216
	s_waitcnt lgkmcnt(3)
	v_mfma_f32_16x16x32_bf16 v[94:97], v[136:139], v[152:155], v[94:97]
	v_cvt_pk_bf16_f32 v158, v166, v184
	v_cvt_pk_bf16_f32 v159, v214, v218
	s_waitcnt lgkmcnt(2)
	v_mfma_f32_16x16x32_bf16 v[90:93], v[140:143], v[152:155], v[90:93]
	v_cvt_pk_bf16_f32 v170, v117, v221
	v_cvt_pk_bf16_f32 v171, v119, v223
	v_mfma_f32_16x16x32_bf16 v[78:81], v[136:139], v[156:159], v[78:81]
	v_cvt_pk_bf16_f32 v172, v109, v113
	v_cvt_pk_bf16_f32 v173, v111, v115
	v_mfma_f32_16x16x32_bf16 v[74:77], v[140:143], v[156:159], v[74:77]
	v_cvt_pk_bf16_f32 v98, v116, v220
	v_cvt_pk_bf16_f32 v99, v118, v222
	v_mfma_f32_16x16x32_bf16 v[62:65], v[136:139], v[170:173], v[62:65]
	v_cvt_pk_bf16_f32 v100, v108, v112
	v_cvt_pk_bf16_f32 v101, v110, v114
	v_mfma_f32_16x16x32_bf16 v[58:61], v[140:143], v[170:173], v[58:61]
	v_pk_add_f32 v[160:161], v[160:161], v[178:179]
	v_pk_add_f32 v[178:179], v[212:213], v[216:217]
	v_mfma_f32_16x16x32_bf16 v[38:41], v[136:139], v[98:101], v[38:41]
	v_pk_add_f32 v[160:161], v[160:161], v[178:179]
	ds_read_b128 v[136:139], v165 offset:4608
	v_mfma_f32_16x16x32_bf16 v[34:37], v[140:143], v[98:101], v[34:37]
	v_pk_add_f32 v[166:167], v[166:167], v[184:185]
	ds_read_b128 v[140:143], v165 offset:5120
	s_waitcnt lgkmcnt(3)
	v_mfma_f32_16x16x32_bf16 v[86:89], v[144:147], v[152:155], v[86:89]
	v_pk_add_f32 v[178:179], v[214:215], v[218:219]
	v_pk_add_f32 v[166:167], v[166:167], v[178:179]
	v_mfma_f32_16x16x32_bf16 v[70:73], v[144:147], v[156:159], v[70:73]
	v_pk_add_f32 v[160:161], v[160:161], v[166:167]
	v_pk_add_f32 v[106:107], v[106:107], v[160:161]
	v_mfma_f32_16x16x32_bf16 v[54:57], v[144:147], v[170:173], v[54:57]
	v_pk_add_f32 v[116:117], v[116:117], v[220:221]
	v_pk_add_f32 v[118:119], v[118:119], v[222:223]
	v_mfma_f32_16x16x32_bf16 v[30:33], v[144:147], v[98:101], v[30:33]
	v_pk_add_f32 v[108:109], v[108:109], v[112:113]
	ds_read_b128 v[144:147], v165 offset:6912
	s_waitcnt lgkmcnt(2)
	v_mfma_f32_16x16x32_bf16 v[174:177], v[136:139], v[2:5], v[228:231]
	v_pk_add_f32 v[110:111], v[110:111], v[114:115]
	v_pk_add_f32 v[116:117], v[116:117], v[118:119]
	v_mfma_f32_16x16x32_bf16 v[196:199], v[136:139], v[10:13], v[232:235]
	v_pk_add_f32 v[108:109], v[108:109], v[110:111]
	v_pk_add_f32 v[108:109], v[116:117], v[108:109]
	v_mfma_f32_16x16x32_bf16 v[204:207], v[136:139], v[18:21], v[236:239]
	v_pk_add_f32 v[104:105], v[104:105], v[108:109]
	v_mfma_f32_16x16x32_bf16 v[136:139], v[136:139], v[42:45], v[240:243]
	s_waitcnt lgkmcnt(0)
; DI unsigned pk2(float lo, float hi) { f32x2 v = {lo, hi}; bf16x2_t b = __builtin_convertvector(v, bf16x2_t); return __builtin_bit_cast(unsigned, b); }
; #define MFMA16(a, b, c) __builtin_amdgcn_mfma_f32_16x16x32_bf16((a), (b), (c), 0, 0, 0)
; #define LDS_V(sv, db, cb) lds_v((sv), 2 * (db) * AT_GRP + (cb) * 128)
; DI void attn_group4(f32x4 (&o)[4][4], const float (&mref)[4], float (&ls)[4], const bf16x8 (&q)[4][2], bf16x8 k00, bf16x8 k01, bf16x8 k10, bf16x8 k11,
;                     bf16x8 v0, bf16x8 v1, bf16x8 v2, bf16x8 v3) {
;     const f32x4 z = {0.f, 0.f, 0.f, 0.f};
;     constexpr float C = 0.125f * LOG2E;
;     f32x4 s0[4], s1[4];
;     __builtin_amdgcn_s_setprio(1);
; #pragma unroll
;     for (int h = 0; h < 4; ++h) { s0[h] = MFMA16(k00, q[h][0], z); s1[h] = MFMA16(k10, q[h][0], z); }
; #pragma unroll
;     for (int h = 0; h < 4; ++h) { s0[h] = MFMA16(k01, q[h][1], s0[h]); s1[h] = MFMA16(k11, q[h][1], s1[h]); }
;     __builtin_amdgcn_s_setprio(0);
;     bf16x8 pb[4];
; #pragma unroll
;     for (int h = 0; h < 4; ++h) {
;         f32x4 p0, p1;
; #pragma unroll
;         for (int e = 0; e < 4; ++e) { p0[e] = __builtin_amdgcn_exp2f(__builtin_fmaf(s0[h][e], C, -mref[h])); p1[e] = __builtin_amdgcn_exp2f(__builtin_fmaf(s1[h][e], C, -mref[h])); }
;         ls[h] += ((p0[0] + p0[1]) + (p0[2] + p0[3])) + ((p1[0] + p1[1]) + (p1[2] + p1[3]));
;         u32x4 pw; pw.x = pk2(p0[0], p0[1]); pw.y = pk2(p0[2], p0[3]); pw.z = pk2(p1[0], p1[1]); pw.w = pk2(p1[2], p1[3]);
;         pb[h] = __builtin_bit_cast(bf16x8, pw);
;     }
;     __builtin_amdgcn_s_setprio(1);
; #pragma unroll
;     for (int h = 0; h < 4; ++h) { o[h][0] = MFMA16(v0, pb[h], o[h][0]); o[h][1] = MFMA16(v1, pb[h], o[h][1]); o[h][2] = MFMA16(v2, pb[h], o[h][2]); o[h][3] = MFMA16(v3, pb[h], o[h][3]); }
;     __builtin_amdgcn_s_setprio(0);
; }
; DI void attn_odd_lds(Frame& F, const float* gk  , const float* gq  , bool with_ctx) {
;     ...
;             for (int hf = 0; hf < 2; ++hf) {
;                 const bf16x8 k00 = LDS_K(sk, hf * 32, 0, 0), k01 = LDS_K(sk, hf * 32, 0, 1), k10 = LDS_K(sk, hf * 32, 1, 0), k11 = LDS_K(sk, hf * 32, 1, 1);
;                 const bf16x8 v0 = LDS_V(sv, 0, hf * 4), v1 = LDS_V(sv, 1, hf * 4), v2 = LDS_V(sv, 2, hf * 4), v3 = LDS_V(sv, 3, hf * 4);
;                 attn_group4(o, mx, ls, q, k00, k01, k10, k11, v0, v1, v2, v3);
;             }
	v_mfma_f32_16x16x32_bf16 v[188:191], v[144:147], v[2:5], v[228:231]
	v_mfma_f32_16x16x32_bf16 v[200:203], v[144:147], v[10:13], v[232:235]
	v_mfma_f32_16x16x32_bf16 v[208:211], v[144:147], v[18:21], v[236:239]
	v_mfma_f32_16x16x32_bf16 v[82:85], v[148:151], v[152:155], v[82:85]
	v_add_u32_e32 v152, 0x2c00, v168
	v_mfma_f32_16x16x32_bf16 v[66:69], v[148:151], v[156:159], v[66:69]
	v_add_u32_e32 v156, 0x3800, v168
	v_mfma_f32_16x16x32_bf16 v[50:53], v[148:151], v[170:173], v[50:53]
	v_mfma_f32_16x16x32_bf16 v[26:29], v[148:151], v[98:101], v[26:29]
	v_mfma_f32_16x16x32_bf16 v[174:177], v[140:143], v[6:9], v[174:177]
	ds_read_b128 v[148:151], v165 offset:7424
	ds_read2_b64 v[98:101], v195 offset0:192 offset1:224
	v_mfma_f32_16x16x32_bf16 v[144:147], v[144:147], v[42:45], v[240:243]
	ds_read2_b64 v[152:155], v152 offset0:96 offset1:128
	ds_read2_b64 v[156:159], v156 offset1:32
	v_mfma_f32_16x16x32_bf16 v[196:199], v[140:143], v[14:17], v[196:199]
	v_add_u32_e32 v165, 0x4000, v168
	ds_read2_b64 v[170:173], v165 offset0:32 offset1:64
	v_mfma_f32_16x16x32_bf16 v[204:207], v[140:143], v[22:25], v[204:207]
	v_exp_f32_e32 v225, v176
	v_exp_f32_e32 v175, v175
	v_mfma_f32_16x16x32_bf16 v[136:139], v[140:143], v[46:49], v[136:139]
	v_exp_f32_e32 v177, v177
	s_waitcnt lgkmcnt(4)
	v_mfma_f32_16x16x32_bf16 v[188:191], v[148:151], v[6:9], v[188:191]
	v_exp_f32_e32 v224, v198
	v_exp_f32_e32 v176, v199
	v_mfma_f32_16x16x32_bf16 v[200:203], v[148:151], v[14:17], v[200:203]
	v_pk_add_f32 v[166:167], v[224:225], v[176:177]
	v_mfma_f32_16x16x32_bf16 v[208:211], v[148:151], v[22:25], v[208:211]
	v_mfma_f32_16x16x32_bf16 v[140:143], v[148:151], v[46:49], v[144:147]
	v_exp_f32_e32 v149, v174
	v_exp_f32_e32 v174, v197
	v_exp_f32_e32 v148, v196
	v_exp_f32_e32 v151, v188
	v_exp_f32_e32 v227, v190
	v_exp_f32_e32 v189, v189
	v_exp_f32_e32 v188, v201
	v_exp_f32_e32 v226, v202
	v_exp_f32_e32 v191, v191
	v_exp_f32_e32 v150, v200
	v_exp_f32_e32 v190, v203
	v_pk_add_f32 v[160:161], v[148:149], v[174:175]
	v_pk_add_f32 v[160:161], v[160:161], v[166:167]
	v_pk_add_f32 v[178:179], v[226:227], v[190:191]
	v_pk_add_f32 v[166:167], v[150:151], v[188:189]
	v_pk_add_f32 v[166:167], v[166:167], v[178:179]
	v_pk_add_f32 v[160:161], v[160:161], v[166:167]
	v_cvt_pk_bf16_f32 v146, v151, v189
	v_cvt_pk_bf16_f32 v150, v150, v188
	v_pk_add_f32 v[106:107], v[106:107], v[160:161]
	v_exp_f32_e32 v161, v204
	v_exp_f32_e32 v179, v205
	v_exp_f32_e32 v189, v206
	v_exp_f32_e32 v197, v207
	v_exp_f32_e32 v160, v136
	v_exp_f32_e32 v178, v137
	v_exp_f32_e32 v188, v138
	v_exp_f32_e32 v196, v139
	v_cvt_pk_bf16_f32 v147, v227, v191
	v_cvt_pk_bf16_f32 v151, v226, v190
	v_exp_f32_e32 v167, v208
	v_exp_f32_e32 v185, v209
	v_exp_f32_e32 v191, v210
	v_exp_f32_e32 v199, v211
	v_exp_f32_e32 v166, v140
	v_exp_f32_e32 v184, v141
	v_exp_f32_e32 v190, v142
	v_exp_f32_e32 v198, v143
	v_pk_add_f32 v[110:111], v[188:189], v[196:197]
	v_pk_add_f32 v[108:109], v[160:161], v[178:179]
	v_pk_add_f32 v[108:109], v[108:109], v[110:111]
	v_pk_add_f32 v[112:113], v[190:191], v[198:199]
	v_pk_add_f32 v[110:111], v[166:167], v[184:185]
	v_pk_add_f32 v[110:111], v[110:111], v[112:113]
	v_cvt_pk_bf16_f32 v144, v149, v175
	v_pk_add_f32 v[108:109], v[108:109], v[110:111]
	v_cvt_pk_bf16_f32 v145, v225, v177
	v_cvt_pk_bf16_f32 v148, v148, v174
	v_cvt_pk_bf16_f32 v149, v224, v176
	s_waitcnt lgkmcnt(3)
	v_mfma_f32_16x16x32_bf16 v[94:97], v[98:101], v[144:147], v[94:97]
	v_pk_add_f32 v[104:105], v[104:105], v[108:109]
	v_cvt_pk_bf16_f32 v174, v161, v179
	s_waitcnt lgkmcnt(2)
	v_mfma_f32_16x16x32_bf16 v[90:93], v[152:155], v[144:147], v[90:93]
	v_cvt_pk_bf16_f32 v175, v189, v197
	v_cvt_pk_bf16_f32 v176, v167, v185
	s_waitcnt lgkmcnt(1)
	v_mfma_f32_16x16x32_bf16 v[86:89], v[156:159], v[144:147], v[86:89]
	v_cvt_pk_bf16_f32 v177, v191, v199
	v_cvt_pk_bf16_f32 v108, v160, v178
	s_waitcnt lgkmcnt(0)
	v_mfma_f32_16x16x32_bf16 v[82:85], v[170:173], v[144:147], v[82:85]
	v_cvt_pk_bf16_f32 v109, v188, v196
	v_cvt_pk_bf16_f32 v110, v166, v184
	v_mfma_f32_16x16x32_bf16 v[78:81], v[98:101], v[148:151], v[78:81]
	v_cvt_pk_bf16_f32 v111, v190, v198
	v_mfma_f32_16x16x32_bf16 v[74:77], v[152:155], v[148:151], v[74:77]
	v_mfma_f32_16x16x32_bf16 v[70:73], v[156:159], v[148:151], v[70:73]
	v_mfma_f32_16x16x32_bf16 v[66:69], v[170:173], v[148:151], v[66:69]
	v_mfma_f32_16x16x32_bf16 v[62:65], v[98:101], v[174:177], v[62:65]
	v_mfma_f32_16x16x32_bf16 v[58:61], v[152:155], v[174:177], v[58:61]
	v_mfma_f32_16x16x32_bf16 v[54:57], v[156:159], v[174:177], v[54:57]
	v_mfma_f32_16x16x32_bf16 v[50:53], v[170:173], v[174:177], v[50:53]
	v_mfma_f32_16x16x32_bf16 v[38:41], v[98:101], v[108:111], v[38:41]
	v_mfma_f32_16x16x32_bf16 v[34:37], v[152:155], v[108:111], v[34:37]
	v_mfma_f32_16x16x32_bf16 v[30:33], v[156:159], v[108:111], v[30:33]
	v_mfma_f32_16x16x32_bf16 v[26:29], v[170:173], v[108:111], v[26:29]
	s_setprio 0
	s_add_i32 s17, s17, 1
	s_add_i32 s39, s39, 64
	s_cmp_eq_u32 s37, s17
	s_cbranch_scc1 .LBB0_240
